# final norm: all x and gamma loads of a row issued up front, counted vmcnt instead of vmcnt(0) after each store
# speedup vs baseline: 1.0256x; 1.0009x over previous
; __device__ __forceinline__ void final_norm_phase(const Params& p) {
;     ...
;   for (int row = blockIdx.x * 8 + wave; row < 65536; row += gridDim.x * 8) {
;     float* xr = p.out + (size_t)row * DM;
;     float4 v[4]; float ss = 0;
; #pragma unroll
;     for (int i = 0; i < 4; ++i) { v[i] = *(const float4*)(xr + lane * 4 + i * 256); ss += v[i].x * v[i].x + v[i].y * v[i].y + v[i].z * v[i].z + v[i].w * v[i].w; }
;     ss = wave_sum(ss);
;     float rstd = rsqrtf(ss * (1.f / 1024.f) + 1e-6f);
; #pragma unroll
;     for (int i = 0; i < 4; ++i) {
;       int col = lane * 4 + i * 256; float4 gg = *(const float4*)(g + col);
;       float4 o; o.x = v[i].x * rstd * gg.x; o.y = v[i].y * rstd * gg.y; o.z = v[i].z * rstd * gg.z; o.w = v[i].w * rstd * gg.w;
;       *(float4*)(xr + col) = o;
;     }
.LBB0_74:
	v_ashrrev_i32_e32 v1, 31, v0
	v_lshlrev_b64 v[12:13], 12, v[0:1]
	v_lshl_add_u64 v[32:33], v[4:5], 0, v[12:13]
	global_load_dwordx4 v[12:15], v[32:33], off
	global_load_dwordx4 v[20:23], v[32:33], off offset:1024
	global_load_dwordx4 v[24:27], v[32:33], off offset:2048
	global_load_dwordx4 v[28:31], v[32:33], off offset:3072
	global_load_dwordx4 v[16:19], v[2:3], off
	global_load_dwordx4 v[42:45], v[2:3], off offset:1024
	global_load_dwordx4 v[46:49], v[2:3], off offset:2048
	global_load_dwordx4 v[50:53], v[2:3], off offset:3072
	s_waitcnt lgkmcnt(0)
	v_add_u32_e32 v0, s25, v0
	s_mov_b32 s2, 0xffff
	s_waitcnt vmcnt(7)
	v_mov_b32_e32 v56, v13
	v_mov_b32_e32 v54, v12
	s_waitcnt vmcnt(6)
	v_mov_b32_e32 v57, v21
	v_mov_b32_e32 v55, v20
	v_pk_mul_f32 v[56:57], v[56:57], v[56:57]
	v_mov_b32_e32 v58, v15
	v_pk_fma_f32 v[54:55], v[54:55], v[54:55], v[56:57]
	v_mov_b32_e32 v56, v14
	v_mov_b32_e32 v57, v22
	v_mov_b32_e32 v59, v23
	v_pk_fma_f32 v[54:55], v[56:57], v[56:57], v[54:55]
	s_nop 0
	v_pk_fma_f32 v[34:35], v[58:59], v[58:59], v[54:55]
	s_nop 0
	v_add_f32_e32 v1, v34, v35
	s_waitcnt vmcnt(5)
	v_mov_b32_e32 v38, v25
	s_waitcnt vmcnt(4)
	v_mov_b32_e32 v39, v29
	v_mov_b32_e32 v36, v24
	v_mov_b32_e32 v37, v28
	v_pk_mul_f32 v[38:39], v[38:39], v[38:39]
	v_mov_b32_e32 v40, v27
	v_pk_fma_f32 v[36:37], v[36:37], v[36:37], v[38:39]
	v_mov_b32_e32 v38, v26
	v_mov_b32_e32 v39, v30
	v_mov_b32_e32 v41, v31
	v_pk_fma_f32 v[36:37], v[38:39], v[38:39], v[36:37]
	s_nop 0
	v_pk_fma_f32 v[36:37], v[40:41], v[40:41], v[36:37]
	s_nop 0
	v_add_f32_e32 v1, v1, v36
	v_add_f32_e32 v1, v1, v37
	ds_bpermute_b32 v34, v6, v1
	s_waitcnt lgkmcnt(0)
	v_add_f32_e32 v1, v1, v34
	ds_bpermute_b32 v34, v7, v1
	s_waitcnt lgkmcnt(0)
	v_add_f32_e32 v1, v1, v34
	ds_bpermute_b32 v34, v8, v1
	s_waitcnt lgkmcnt(0)
	v_add_f32_e32 v1, v1, v34
	ds_bpermute_b32 v34, v9, v1
	s_waitcnt lgkmcnt(0)
	v_add_f32_e32 v1, v1, v34
	ds_bpermute_b32 v34, v10, v1
	s_waitcnt lgkmcnt(0)
	v_add_f32_e32 v1, v1, v34
	ds_bpermute_b32 v34, v11, v1
	s_waitcnt lgkmcnt(0)
	v_add_f32_e32 v1, v1, v34
	v_fmamk_f32 v1, v1, 0x3a800000, v162
	v_cmp_gt_f32_e32 vcc, s7, v1
	v_mul_f32_e32 v34, 0x4b800000, v1
	s_nop 0
	v_cndmask_b32_e32 v1, v1, v34, vcc
	v_rsq_f32_e32 v1, v1
	s_nop 0
	v_mul_f32_e32 v34, 0x45800000, v1
	v_cndmask_b32_e32 v34, v1, v34, vcc
	v_pk_mul_f32 v[12:13], v[12:13], v[34:35] op_sel_hi:[1,0]
	v_pk_mul_f32 v[14:15], v[14:15], v[34:35] op_sel_hi:[1,0]
	s_waitcnt vmcnt(3)
	v_pk_mul_f32 v[12:13], v[16:17], v[12:13]
	v_pk_mul_f32 v[14:15], v[18:19], v[14:15]
	global_store_dwordx4 v[32:33], v[12:15], off
	v_pk_mul_f32 v[16:17], v[20:21], v[34:35] op_sel_hi:[1,0]
	v_cmp_lt_i32_e32 vcc, s2, v0
	s_or_b64 s[4:5], vcc, s[4:5]
	s_waitcnt vmcnt(3)
	v_pk_mul_f32 v[42:43], v[42:43], v[16:17]
	v_pk_mul_f32 v[16:17], v[22:23], v[34:35] op_sel_hi:[1,0]
	s_nop 0
	v_pk_mul_f32 v[44:45], v[44:45], v[16:17]
	global_store_dwordx4 v[32:33], v[42:45], off offset:1024
	v_pk_mul_f32 v[16:17], v[24:25], v[34:35] op_sel_hi:[1,0]
	s_waitcnt vmcnt(3)
	v_pk_mul_f32 v[46:47], v[16:17], v[46:47]
	v_pk_mul_f32 v[16:17], v[26:27], v[34:35] op_sel_hi:[1,0]
	s_nop 0
	v_pk_mul_f32 v[48:49], v[16:17], v[48:49]
	global_store_dwordx4 v[32:33], v[46:49], off offset:2048
	v_pk_mul_f32 v[16:17], v[28:29], v[34:35] op_sel_hi:[1,0]
	s_waitcnt vmcnt(3)
	v_pk_mul_f32 v[50:51], v[16:17], v[50:51]
	v_pk_mul_f32 v[16:17], v[30:31], v[34:35] op_sel_hi:[1,0]
	s_nop 0
	v_pk_mul_f32 v[52:53], v[16:17], v[52:53]
	global_store_dwordx4 v[32:33], v[50:53], off offset:3072
	s_andn2_b64 exec, exec, s[4:5]
	s_cbranch_execnz .LBB0_74
